# NSA_PACK gather-GEMM k-loop (lone block per CU): LDS reads first, six LDS-DMA groups spread through the MFMA ladder, DMA address temps moved off the fragment registers
# baseline (speedup 1.0000x reference)
.LBB0_596:
	v_mov_b32_e32 v197, 0
	s_mul_i32 s69, s13, 0x6000
	s_add_i32 s70, s69, 0xffffa000
	s_cmp_gt_i32 s13, 0
	s_cselect_b32 s74, s70, 0xc000
	s_lshr_b32 s75, s40, 1
	v_and_or_b32 v196, s43, 32, v143
	v_add_u32_e32 v149, s75, v144
	v_mad_i64_i32 v[194:195], s[70:71], v149, s16, v[130:131]
	v_lshlrev_b32_e32 v196, 1, v196
	v_lshl_add_u64 v[194:195], v[194:195], 0, v[196:197]
	s_waitcnt vmcnt(6)
	v_lshl_add_u64 v[194:195], v[194:195], 0, s[66:67]
	s_add_i32 s70, s74, s68
	v_add_u32_e32 v149, s75, v145
	s_waitcnt lgkmcnt(0)
	s_barrier
	v_or_b32_e32 v0, s69, v147
	v_add_u32_e32 v0, v0, v146
	ds_read_b128 v[150:153], v0
	ds_read_b128 v[154:157], v0 offset:1024
	ds_read_b128 v[158:161], v0 offset:2048
	ds_read_b128 v[162:165], v0 offset:3072
	v_add3_u32 v0, s69, v148, v146
	ds_read_b128 v[166:169], v0 offset:8192
	ds_read_b128 v[170:173], v0 offset:9216
	ds_read_b128 v[174:177], v0 offset:10240
	ds_read_b128 v[178:181], v0 offset:11264
	ds_read_b128 v[182:185], v0 offset:12288
	ds_read_b128 v[186:189], v0 offset:13312
	ds_read_b128 v[190:193], v0 offset:14336
	ds_read_b128 v[198:201], v0 offset:15360
	s_waitcnt lgkmcnt(7)
	v_mfma_f32_16x16x32_bf16 v[126:129], v[166:169], v[150:153], v[126:129]
	v_mfma_f32_16x16x32_bf16 v[122:125], v[166:169], v[154:157], v[122:125]
	v_mfma_f32_16x16x32_bf16 v[118:121], v[166:169], v[158:161], v[118:121]
	v_mfma_f32_16x16x32_bf16 v[114:117], v[166:169], v[162:165], v[114:117]
	s_mov_b32 s71, m0
	s_mov_b32 m0, s70
	s_nop 0
	global_load_lds_dwordx4 v[194:195], off
	s_mov_b32 m0, s71
	s_waitcnt lgkmcnt(6)
	v_mfma_f32_16x16x32_bf16 v[110:113], v[170:173], v[150:153], v[110:113]
	v_mfma_f32_16x16x32_bf16 v[106:109], v[170:173], v[154:157], v[106:109]
	v_mfma_f32_16x16x32_bf16 v[102:105], v[170:173], v[158:161], v[102:105]
	v_mfma_f32_16x16x32_bf16 v[98:101], v[170:173], v[162:165], v[98:101]
	s_waitcnt lgkmcnt(5)
	v_mfma_f32_16x16x32_bf16 v[94:97], v[174:177], v[150:153], v[94:97]
	s_nop 0
	v_mad_i64_i32 v[194:195], s[70:71], v149, s16, v[130:131]
	v_lshl_add_u64 v[194:195], v[194:195], 0, v[196:197]
	v_lshl_add_u64 v[194:195], v[194:195], 0, s[66:67]
	s_add_i32 s70, s74, s41
	s_mov_b32 s71, m0
	s_mov_b32 m0, s70
	s_nop 0
	global_load_lds_dwordx4 v[194:195], off
	s_mov_b32 m0, s71
	v_mfma_f32_16x16x32_bf16 v[90:93], v[174:177], v[154:157], v[90:93]
	v_mfma_f32_16x16x32_bf16 v[86:89], v[174:177], v[158:161], v[86:89]
	v_mfma_f32_16x16x32_bf16 v[82:85], v[174:177], v[162:165], v[82:85]
	s_waitcnt lgkmcnt(4)
	v_mfma_f32_16x16x32_bf16 v[78:81], v[178:181], v[150:153], v[78:81]
	v_mfma_f32_16x16x32_bf16 v[74:77], v[178:181], v[154:157], v[74:77]
	s_add_i32 s70, s42, s74
	s_mov_b32 s71, m0
	s_mov_b32 m0, s70
	s_nop 0
	global_load_lds_dwordx4 v[138:139], off
	s_mov_b32 m0, s71
	v_mfma_f32_16x16x32_bf16 v[70:73], v[178:181], v[158:161], v[70:73]
	v_mfma_f32_16x16x32_bf16 v[66:69], v[178:181], v[162:165], v[66:69]
	s_waitcnt lgkmcnt(3)
	v_mfma_f32_16x16x32_bf16 v[62:65], v[182:185], v[150:153], v[62:65]
	v_mfma_f32_16x16x32_bf16 v[58:61], v[182:185], v[154:157], v[58:61]
	v_mfma_f32_16x16x32_bf16 v[54:57], v[182:185], v[158:161], v[54:57]
	s_add_i32 s71, s70, 0x400
	s_mov_b32 s74, m0
	s_mov_b32 m0, s71
	s_nop 0
	global_load_lds_dwordx4 v[136:137], off
	s_mov_b32 m0, s74
	v_mfma_f32_16x16x32_bf16 v[50:53], v[182:185], v[162:165], v[50:53]
	s_waitcnt lgkmcnt(2)
	v_mfma_f32_16x16x32_bf16 v[46:49], v[186:189], v[150:153], v[46:49]
	v_mfma_f32_16x16x32_bf16 v[42:45], v[186:189], v[154:157], v[42:45]
	v_mfma_f32_16x16x32_bf16 v[38:41], v[186:189], v[158:161], v[38:41]
	v_mfma_f32_16x16x32_bf16 v[34:37], v[186:189], v[162:165], v[34:37]
	s_add_i32 s71, s70, 0x800
	s_mov_b32 s74, m0
	s_mov_b32 m0, s71
	s_nop 0
	global_load_lds_dwordx4 v[134:135], off
	s_mov_b32 m0, s74
	s_waitcnt lgkmcnt(1)
	v_mfma_f32_16x16x32_bf16 v[30:33], v[190:193], v[150:153], v[30:33]
	v_mfma_f32_16x16x32_bf16 v[26:29], v[190:193], v[154:157], v[26:29]
	v_mfma_f32_16x16x32_bf16 v[22:25], v[190:193], v[158:161], v[22:25]
	v_mfma_f32_16x16x32_bf16 v[18:21], v[190:193], v[162:165], v[18:21]
	s_waitcnt lgkmcnt(0)
	v_mfma_f32_16x16x32_bf16 v[14:17], v[198:201], v[150:153], v[14:17]
	s_addk_i32 s70, 0xc00
	s_mov_b32 s71, m0
	s_mov_b32 m0, s70
	s_nop 0
	global_load_lds_dwordx4 v[132:133], off
	s_mov_b32 m0, s71
	v_mfma_f32_16x16x32_bf16 v[10:13], v[198:201], v[154:157], v[10:13]
	v_mfma_f32_16x16x32_bf16 v[6:9], v[198:201], v[158:161], v[6:9]
	v_mfma_f32_16x16x32_bf16 v[2:5], v[198:201], v[162:165], v[2:5]
	s_add_i32 s69, s13, 1
	s_cmp_lg_u32 s13, 2
	s_cselect_b32 s13, s69, 0
	s_add_i32 s40, s40, 1
	s_add_i32 s43, s43, 32
	v_lshl_add_u64 v[132:133], v[132:133], 0, 64
	v_lshl_add_u64 v[134:135], v[134:135], 0, 64
	v_lshl_add_u64 v[136:137], v[136:137], 0, 64
	s_cmp_eq_u32 s40, 64
	v_lshl_add_u64 v[138:139], v[138:139], 0, 64
	s_cbranch_scc0 .LBB0_596
	s_waitcnt vmcnt(6)
	v_add_u32_e32 v0, v148, v146
	s_waitcnt lgkmcnt(0)
	s_barrier
	ds_read_b128 v[130:133], v0 offset:64512
	ds_read_b128 v[134:137], v0 offset:63488
	ds_read_b128 v[148:151], v0 offset:62464
	ds_read_b128 v[152:155], v0 offset:61440
	ds_read_b128 v[156:159], v0 offset:60416
	ds_read_b128 v[160:163], v0 offset:59392
	ds_read_b128 v[164:167], v0 offset:58368
	ds_read_b128 v[168:171], v0 offset:57344
	v_add_u32_e32 v138, v147, v146
	ds_read_b128 v[144:147], v138 offset:52224
	ds_read_b128 v[172:175], v138 offset:51200
	ds_read_b128 v[176:179], v138 offset:50176
	ds_read_b128 v[180:183], v138 offset:49152
	s_lshl_b32 s40, s0, 8
	s_lshl_b64 s[0:1], s[0:1], 15
	s_ashr_i32 s41, s40, 31
	s_waitcnt lgkmcnt(0)
	v_mfma_f32_16x16x32_bf16 v[126:129], v[168:171], v[180:183], v[126:129]
	v_mfma_f32_16x16x32_bf16 v[46:49], v[148:151], v[180:183], v[46:49]
	v_mfma_f32_16x16x32_bf16 v[42:45], v[148:151], v[176:179], v[42:45]
	v_mfma_f32_16x16x32_bf16 v[38:41], v[148:151], v[172:175], v[38:41]
	v_mfma_f32_16x16x32_bf16 v[34:37], v[148:151], v[144:147], v[34:37]
	v_mfma_f32_16x16x32_bf16 v[30:33], v[134:137], v[180:183], v[30:33]
	v_mfma_f32_16x16x32_bf16 v[26:29], v[134:137], v[176:179], v[26:29]
	v_mfma_f32_16x16x32_bf16 v[22:25], v[134:137], v[172:175], v[22:25]
	v_mfma_f32_16x16x32_bf16 v[18:21], v[134:137], v[144:147], v[18:21]
	v_mfma_f32_16x16x32_bf16 v[14:17], v[130:133], v[180:183], v[14:17]
	v_mfma_f32_16x16x32_bf16 v[10:13], v[130:133], v[176:179], v[10:13]
	v_mfma_f32_16x16x32_bf16 v[6:9], v[130:133], v[172:175], v[6:9]
	v_mfma_f32_16x16x32_bf16 v[2:5], v[130:133], v[144:147], v[2:5]
	v_mfma_f32_16x16x32_bf16 v[122:125], v[168:171], v[176:179], v[122:125]
	v_mfma_f32_16x16x32_bf16 v[118:121], v[168:171], v[172:175], v[118:121]
	v_mfma_f32_16x16x32_bf16 v[114:117], v[168:171], v[144:147], v[114:117]
	v_mfma_f32_16x16x32_bf16 v[110:113], v[164:167], v[180:183], v[110:113]
	v_mfma_f32_16x16x32_bf16 v[106:109], v[164:167], v[176:179], v[106:109]
	v_mfma_f32_16x16x32_bf16 v[102:105], v[164:167], v[172:175], v[102:105]
	v_mfma_f32_16x16x32_bf16 v[98:101], v[164:167], v[144:147], v[98:101]
	v_mfma_f32_16x16x32_bf16 v[94:97], v[160:163], v[180:183], v[94:97]
	v_mfma_f32_16x16x32_bf16 v[90:93], v[160:163], v[176:179], v[90:93]
	v_mfma_f32_16x16x32_bf16 v[86:89], v[160:163], v[172:175], v[86:89]
	v_mfma_f32_16x16x32_bf16 v[82:85], v[160:163], v[144:147], v[82:85]
	v_mfma_f32_16x16x32_bf16 v[78:81], v[156:159], v[180:183], v[78:81]
	v_mfma_f32_16x16x32_bf16 v[74:77], v[156:159], v[176:179], v[74:77]
	v_mfma_f32_16x16x32_bf16 v[70:73], v[156:159], v[172:175], v[70:73]
	v_mfma_f32_16x16x32_bf16 v[66:69], v[156:159], v[144:147], v[66:69]
	v_mfma_f32_16x16x32_bf16 v[62:65], v[152:155], v[180:183], v[62:65]
	v_mfma_f32_16x16x32_bf16 v[58:61], v[152:155], v[176:179], v[58:61]
	v_mfma_f32_16x16x32_bf16 v[54:57], v[152:155], v[172:175], v[54:57]
	v_mfma_f32_16x16x32_bf16 v[50:53], v[152:155], v[144:147], v[50:53]
	s_waitcnt vmcnt(0)
	s_waitcnt lgkmcnt(0)
	s_barrier
	ds_read_b128 v[130:133], v138
	ds_read_b128 v[134:137], v138 offset:1024
	ds_read_b128 v[144:147], v138 offset:2048
	ds_read_b128 v[148:151], v138 offset:3072
	ds_read_b128 v[152:155], v0 offset:8192
	ds_read_b128 v[156:159], v0 offset:9216
	ds_read_b128 v[160:163], v0 offset:10240
	ds_read_b128 v[164:167], v0 offset:11264
	ds_read_b128 v[168:171], v0 offset:12288
	ds_read_b128 v[172:175], v0 offset:13312
	ds_read_b128 v[176:179], v0 offset:14336
	ds_read_b128 v[180:183], v0 offset:15360
	s_lshl_b64 s[40:41], s[40:41], 2
	s_add_u32 s42, s14, s40
	s_addc_u32 s43, s15, s41
	s_add_u32 s40, s53, s0
	s_addc_u32 s41, s54, s1
	s_waitcnt lgkmcnt(2)
	v_mfma_f32_16x16x32_bf16 v[46:49], v[172:175], v[130:133], v[46:49]
	v_mfma_f32_16x16x32_bf16 v[42:45], v[172:175], v[134:137], v[42:45]
	v_mfma_f32_16x16x32_bf16 v[38:41], v[172:175], v[144:147], v[38:41]
	v_mfma_f32_16x16x32_bf16 v[34:37], v[172:175], v[148:151], v[34:37]
	s_waitcnt lgkmcnt(1)
	v_mfma_f32_16x16x32_bf16 v[30:33], v[176:179], v[130:133], v[30:33]
	v_mfma_f32_16x16x32_bf16 v[26:29], v[176:179], v[134:137], v[26:29]
	v_mfma_f32_16x16x32_bf16 v[22:25], v[176:179], v[144:147], v[22:25]
	v_mfma_f32_16x16x32_bf16 v[18:21], v[176:179], v[148:151], v[18:21]
	s_waitcnt lgkmcnt(0)
	v_mfma_f32_16x16x32_bf16 v[14:17], v[180:183], v[130:133], v[14:17]
	v_mfma_f32_16x16x32_bf16 v[10:13], v[180:183], v[134:137], v[10:13]
	v_mfma_f32_16x16x32_bf16 v[6:9], v[180:183], v[144:147], v[6:9]
	v_mfma_f32_16x16x32_bf16 v[2:5], v[180:183], v[148:151], v[2:5]
	v_mfma_f32_16x16x32_bf16 v[184:187], v[152:155], v[130:133], v[126:129]
	v_mfma_f32_16x16x32_bf16 v[122:125], v[152:155], v[134:137], v[122:125]
	v_mfma_f32_16x16x32_bf16 v[188:191], v[152:155], v[144:147], v[118:121]
	v_mfma_f32_16x16x32_bf16 v[114:117], v[152:155], v[148:151], v[114:117]
	v_mfma_f32_16x16x32_bf16 v[110:113], v[156:159], v[130:133], v[110:113]
	v_mfma_f32_16x16x32_bf16 v[106:109], v[156:159], v[134:137], v[106:109]
	v_mfma_f32_16x16x32_bf16 v[102:105], v[156:159], v[144:147], v[102:105]
	v_mfma_f32_16x16x32_bf16 v[98:101], v[156:159], v[148:151], v[98:101]
	v_mfma_f32_16x16x32_bf16 v[94:97], v[160:163], v[130:133], v[94:97]
	v_mfma_f32_16x16x32_bf16 v[90:93], v[160:163], v[134:137], v[90:93]
	v_mfma_f32_16x16x32_bf16 v[86:89], v[160:163], v[144:147], v[86:89]
	v_mfma_f32_16x16x32_bf16 v[82:85], v[160:163], v[148:151], v[82:85]
	v_mfma_f32_16x16x32_bf16 v[78:81], v[164:167], v[130:133], v[78:81]
	v_mfma_f32_16x16x32_bf16 v[74:77], v[164:167], v[134:137], v[74:77]
	v_mfma_f32_16x16x32_bf16 v[70:73], v[164:167], v[144:147], v[70:73]
	v_mfma_f32_16x16x32_bf16 v[66:69], v[164:167], v[148:151], v[66:69]
	v_mfma_f32_16x16x32_bf16 v[62:65], v[168:171], v[130:133], v[62:65]
	v_mfma_f32_16x16x32_bf16 v[58:61], v[168:171], v[134:137], v[58:61]
	v_mfma_f32_16x16x32_bf16 v[54:57], v[168:171], v[144:147], v[54:57]
	v_mfma_f32_16x16x32_bf16 v[50:53], v[168:171], v[148:151], v[50:53]
	v_mov_b32_e32 v129, v224
	s_movk_i32 s0, 0xff80
	v_bfe_u32 v0, v129, 4, 2
	v_lshlrev_b32_e32 v128, 2, v0
	v_and_or_b32 v126, v129, s0, v128
	v_ashrrev_i32_e32 v127, 31, v126
	v_lshl_add_u64 v[118:119], v[126:127], 2, s[42:43]
	s_barrier
	global_load_dwordx4 v[132:135], v[118:119], off
	v_and_b32_e32 v138, 0x4f, v129
	v_lshlrev_b32_e32 v0, 4, v0
	s_movk_i32 s0, 0x210
	s_cmp_gt_u32 s57, 31
	s_waitcnt vmcnt(0)
	v_pk_add_f32 v[120:121], v[184:185], v[132:133]
	s_nop 0
	v_pk_mul_f32 v[130:131], v[120:121], v[120:121]
	v_pk_add_f32 v[122:123], v[122:123], v[132:133]
	v_fmamk_f32 v127, v130, 0xbdd2d3e2, v251
	v_mul_f32_e32 v127, v120, v127
	v_exp_f32_e32 v127, v127
	v_pk_add_f32 v[114:115], v[114:115], v[132:133]
	v_add_f32_e32 v127, 1.0, v127
	v_rcp_f32_e32 v130, v127
	v_fmamk_f32 v127, v131, 0xbdd2d3e2, v251
	v_mul_f32_e32 v127, v121, v127
	v_exp_f32_e32 v127, v127
	s_nop 0
	v_add_f32_e32 v127, 1.0, v127
	v_rcp_f32_e32 v131, v127
	v_mul_u32_u24_e32 v127, 0x210, v138
	v_pk_mul_f32 v[120:121], v[120:121], v[130:131]
	v_pk_add_f32 v[130:131], v[186:187], v[134:135]
	v_cvt_pk_bf16_f32 v120, v120, v121
	v_pk_mul_f32 v[136:137], v[130:131], v[130:131]
	s_nop 0
	v_fmamk_f32 v121, v136, 0xbdd2d3e2, v251
	v_mul_f32_e32 v121, v130, v121
	v_exp_f32_e32 v121, v121
	s_nop 0
	v_add_f32_e32 v121, 1.0, v121
	v_rcp_f32_e32 v136, v121
	v_fmamk_f32 v121, v137, 0xbdd2d3e2, v251
	v_mul_f32_e32 v121, v131, v121
	v_exp_f32_e32 v121, v121
	s_nop 0
	v_add_f32_e32 v121, 1.0, v121
	v_rcp_f32_e32 v137, v121
	s_nop 0
	v_pk_mul_f32 v[130:131], v[130:131], v[136:137]
	s_nop 0
	v_cvt_pk_bf16_f32 v121, v130, v131
	v_lshl_add_u32 v130, v126, 1, v127
	v_pk_mul_f32 v[126:127], v[122:123], v[122:123]
	s_nop 0
	v_fmamk_f32 v126, v126, 0xbdd2d3e2, v251
	v_fmamk_f32 v127, v127, 0xbdd2d3e2, v251
	v_mul_f32_e32 v126, v122, v126
	v_mul_f32_e32 v127, v123, v127
	v_exp_f32_e32 v126, v126
	v_exp_f32_e32 v127, v127
	v_add_f32_e32 v126, 1.0, v126
	v_add_f32_e32 v127, 1.0, v127
	v_rcp_f32_e32 v126, v126
	v_rcp_f32_e32 v127, v127
	s_nop 0
	v_pk_mul_f32 v[122:123], v[122:123], v[126:127]
	s_nop 0
	v_cvt_pk_bf16_f32 v126, v122, v123
	v_pk_add_f32 v[122:123], v[124:125], v[134:135]
	s_nop 0
	v_pk_mul_f32 v[124:125], v[122:123], v[122:123]
	s_nop 0
	v_fmamk_f32 v124, v124, 0xbdd2d3e2, v251
	v_fmamk_f32 v125, v125, 0xbdd2d3e2, v251
	v_mul_f32_e32 v124, v122, v124
	v_mul_f32_e32 v125, v123, v125
	v_exp_f32_e32 v124, v124
	v_exp_f32_e32 v125, v125
	v_add_f32_e32 v124, 1.0, v124
	v_add_f32_e32 v125, 1.0, v125
	v_rcp_f32_e32 v124, v124
	v_rcp_f32_e32 v125, v125
	s_nop 0
	v_pk_mul_f32 v[122:123], v[122:123], v[124:125]
	s_nop 0
	v_cvt_pk_bf16_f32 v127, v122, v123
	v_pk_add_f32 v[122:123], v[188:189], v[132:133]
	s_nop 0
	v_pk_mul_f32 v[124:125], v[122:123], v[122:123]
	s_nop 0
	v_fmamk_f32 v124, v124, 0xbdd2d3e2, v251
	v_fmamk_f32 v125, v125, 0xbdd2d3e2, v251
	v_mul_f32_e32 v124, v122, v124
	v_mul_f32_e32 v125, v123, v125
	v_exp_f32_e32 v124, v124
	v_exp_f32_e32 v125, v125
	v_add_f32_e32 v124, 1.0, v124
	v_add_f32_e32 v125, 1.0, v125
	v_rcp_f32_e32 v124, v124
	v_rcp_f32_e32 v125, v125
	s_nop 0
	v_pk_mul_f32 v[122:123], v[122:123], v[124:125]
	s_nop 0
	v_cvt_pk_bf16_f32 v124, v122, v123
	v_pk_add_f32 v[122:123], v[190:191], v[134:135]
	s_nop 0
	v_pk_mul_f32 v[136:137], v[122:123], v[122:123]
	s_nop 0
	v_fmamk_f32 v125, v136, 0xbdd2d3e2, v251
	v_mul_f32_e32 v125, v122, v125
	v_exp_f32_e32 v125, v125
	s_nop 0
	v_add_f32_e32 v125, 1.0, v125
	v_rcp_f32_e32 v136, v125
	v_fmamk_f32 v125, v137, 0xbdd2d3e2, v251
	v_mul_f32_e32 v125, v123, v125
	v_exp_f32_e32 v125, v125
	s_nop 0
	v_add_f32_e32 v125, 1.0, v125
	v_rcp_f32_e32 v137, v125
	s_nop 0
	v_pk_mul_f32 v[122:123], v[122:123], v[136:137]
	s_nop 0
	v_cvt_pk_bf16_f32 v125, v122, v123
	v_pk_mul_f32 v[122:123], v[114:115], v[114:115]
	s_nop 0
	v_fmamk_f32 v122, v122, 0xbdd2d3e2, v251
	v_fmamk_f32 v123, v123, 0xbdd2d3e2, v251
	v_mul_f32_e32 v122, v114, v122
	v_mul_f32_e32 v123, v115, v123
	v_exp_f32_e32 v122, v122
	v_exp_f32_e32 v123, v123
	v_add_f32_e32 v122, 1.0, v122
	v_add_f32_e32 v123, 1.0, v123
	v_rcp_f32_e32 v122, v122
	v_rcp_f32_e32 v123, v123
	s_nop 0
	v_pk_mul_f32 v[114:115], v[114:115], v[122:123]
	s_nop 0
	v_cvt_pk_bf16_f32 v122, v114, v115
	v_pk_add_f32 v[114:115], v[116:117], v[134:135]
	s_nop 0
	v_pk_mul_f32 v[116:117], v[114:115], v[114:115]
	s_nop 0
	v_fmamk_f32 v116, v116, 0xbdd2d3e2, v251
	v_fmamk_f32 v117, v117, 0xbdd2d3e2, v251
	v_mul_f32_e32 v116, v114, v116
	v_mul_f32_e32 v117, v115, v117
	v_exp_f32_e32 v116, v116
	v_exp_f32_e32 v117, v117
	v_add_f32_e32 v116, 1.0, v116
	v_add_f32_e32 v117, 1.0, v117
	v_rcp_f32_e32 v116, v116
	v_rcp_f32_e32 v117, v117
	s_nop 0
	v_pk_mul_f32 v[114:115], v[114:115], v[116:117]
	s_nop 0
	v_cvt_pk_bf16_f32 v123, v114, v115
	global_load_dwordx4 v[114:117], v[118:119], off offset:64
	s_waitcnt vmcnt(0)
	v_pk_add_f32 v[110:111], v[110:111], v[114:115]
	s_nop 0
	v_pk_mul_f32 v[132:133], v[110:111], v[110:111]
	v_pk_add_f32 v[112:113], v[112:113], v[116:117]
	v_fmamk_f32 v131, v132, 0xbdd2d3e2, v251
	v_mul_f32_e32 v131, v110, v131
	v_exp_f32_e32 v131, v131
	v_pk_add_f32 v[106:107], v[106:107], v[114:115]
	v_pk_add_f32 v[102:103], v[102:103], v[114:115]
	v_pk_add_f32 v[98:99], v[98:99], v[114:115]
	v_add_f32_e32 v131, 1.0, v131
	v_rcp_f32_e32 v132, v131
	v_fmamk_f32 v131, v133, 0xbdd2d3e2, v251
	v_mul_f32_e32 v131, v111, v131
	v_exp_f32_e32 v131, v131
	v_pk_add_f32 v[100:101], v[100:101], v[116:117]
	v_add_f32_e32 v131, 1.0, v131
	v_rcp_f32_e32 v133, v131
	s_nop 0
	v_pk_mul_f32 v[110:111], v[110:111], v[132:133]
	v_pk_mul_f32 v[132:133], v[112:113], v[112:113]
	v_cvt_pk_bf16_f32 v110, v110, v111
	v_fmamk_f32 v111, v132, 0xbdd2d3e2, v251
	v_mul_f32_e32 v111, v112, v111
	v_exp_f32_e32 v111, v111
	s_nop 0
	v_add_f32_e32 v111, 1.0, v111
	v_rcp_f32_e32 v132, v111
	v_fmamk_f32 v111, v133, 0xbdd2d3e2, v251
	v_mul_f32_e32 v111, v113, v111
	v_exp_f32_e32 v111, v111
	s_nop 0
	v_add_f32_e32 v111, 1.0, v111
	v_rcp_f32_e32 v133, v111
	s_nop 0
	v_pk_mul_f32 v[112:113], v[112:113], v[132:133]
	s_nop 0
	v_cvt_pk_bf16_f32 v111, v112, v113
	ds_write2_b64 v130, v[120:121], v[110:111] offset1:4
	v_pk_mul_f32 v[110:111], v[106:107], v[106:107]
	s_nop 0
	v_fmamk_f32 v110, v110, 0xbdd2d3e2, v251
	v_fmamk_f32 v111, v111, 0xbdd2d3e2, v251
	v_mul_f32_e32 v110, v106, v110
	v_mul_f32_e32 v111, v107, v111
	v_exp_f32_e32 v110, v110
	v_exp_f32_e32 v111, v111
	v_add_f32_e32 v110, 1.0, v110
	v_add_f32_e32 v111, 1.0, v111
	v_rcp_f32_e32 v110, v110
	v_rcp_f32_e32 v111, v111
	s_nop 0
	v_pk_mul_f32 v[106:107], v[106:107], v[110:111]
	s_nop 0
	v_cvt_pk_bf16_f32 v110, v106, v107
	v_pk_add_f32 v[106:107], v[108:109], v[116:117]
	s_nop 0
	v_pk_mul_f32 v[108:109], v[106:107], v[106:107]
	s_nop 0
	v_fmamk_f32 v108, v108, 0xbdd2d3e2, v251
	v_fmamk_f32 v109, v109, 0xbdd2d3e2, v251
	v_mul_f32_e32 v108, v106, v108
	v_mul_f32_e32 v109, v107, v109
	v_exp_f32_e32 v108, v108
	v_exp_f32_e32 v109, v109
	v_add_f32_e32 v108, 1.0, v108
	v_add_f32_e32 v109, 1.0, v109
	v_rcp_f32_e32 v108, v108
	v_rcp_f32_e32 v109, v109
	s_nop 0
	v_pk_mul_f32 v[106:107], v[106:107], v[108:109]
	v_pk_mul_f32 v[108:109], v[102:103], v[102:103]
	v_cvt_pk_bf16_f32 v111, v106, v107
	v_fmamk_f32 v107, v108, 0xbdd2d3e2, v251
	v_mul_f32_e32 v107, v102, v107
	v_exp_f32_e32 v107, v107
	v_add_u32_e32 v106, 0x2000, v130
	ds_write2_b64 v106, v[126:127], v[110:111] offset0:32 offset1:36
	v_add_f32_e32 v107, 1.0, v107
	v_rcp_f32_e32 v108, v107
	v_fmamk_f32 v107, v109, 0xbdd2d3e2, v251
	v_mul_f32_e32 v107, v103, v107
	v_exp_f32_e32 v107, v107
	s_nop 0
	v_add_f32_e32 v107, 1.0, v107
	v_rcp_f32_e32 v109, v107
	s_nop 0
	v_pk_mul_f32 v[102:103], v[102:103], v[108:109]
	s_nop 0
	v_cvt_pk_bf16_f32 v108, v102, v103
	v_pk_add_f32 v[102:103], v[104:105], v[116:117]
	s_nop 0
	v_pk_mul_f32 v[104:105], v[102:103], v[102:103]
	s_nop 0
	v_fmamk_f32 v104, v104, 0xbdd2d3e2, v251
	v_fmamk_f32 v105, v105, 0xbdd2d3e2, v251
	v_mul_f32_e32 v104, v102, v104
	v_mul_f32_e32 v105, v103, v105
	v_exp_f32_e32 v104, v104
	v_exp_f32_e32 v105, v105
	v_add_f32_e32 v104, 1.0, v104
	v_add_f32_e32 v105, 1.0, v105
	v_rcp_f32_e32 v104, v104
	v_rcp_f32_e32 v105, v105
	s_nop 0
	v_pk_mul_f32 v[102:103], v[102:103], v[104:105]
	s_nop 0
	v_cvt_pk_bf16_f32 v109, v102, v103
	v_add_u32_e32 v102, 0x4000, v130
	ds_write2_b64 v102, v[124:125], v[108:109] offset0:64 offset1:68
	global_load_dwordx4 v[108:111], v[118:119], off offset:128
	v_pk_mul_f32 v[104:105], v[98:99], v[98:99]
	s_waitcnt vmcnt(0)
	v_pk_add_f32 v[94:95], v[94:95], v[108:109]
	v_fmamk_f32 v103, v104, 0xbdd2d3e2, v251
	v_mul_f32_e32 v103, v98, v103
	v_exp_f32_e32 v103, v103
	v_pk_add_f32 v[90:91], v[90:91], v[108:109]
	v_pk_add_f32 v[86:87], v[86:87], v[108:109]
	v_pk_add_f32 v[82:83], v[82:83], v[108:109]
	v_add_f32_e32 v103, 1.0, v103
	v_rcp_f32_e32 v104, v103
	v_fmamk_f32 v103, v105, 0xbdd2d3e2, v251
	v_mul_f32_e32 v103, v99, v103
	v_exp_f32_e32 v103, v103
	s_nop 0
	v_add_f32_e32 v103, 1.0, v103
	v_rcp_f32_e32 v105, v103
	s_nop 0
	v_pk_mul_f32 v[98:99], v[98:99], v[104:105]
	v_pk_mul_f32 v[104:105], v[100:101], v[100:101]
	v_cvt_pk_bf16_f32 v98, v98, v99
	v_fmamk_f32 v99, v104, 0xbdd2d3e2, v251
	v_mul_f32_e32 v99, v100, v99
	v_exp_f32_e32 v99, v99
	s_nop 0
	v_add_f32_e32 v99, 1.0, v99
	v_rcp_f32_e32 v104, v99
	v_fmamk_f32 v99, v105, 0xbdd2d3e2, v251
	v_mul_f32_e32 v99, v101, v99
	v_exp_f32_e32 v99, v99
	s_nop 0
	v_add_f32_e32 v99, 1.0, v99
	v_rcp_f32_e32 v105, v99
	s_nop 0
	v_pk_mul_f32 v[100:101], v[100:101], v[104:105]
	s_nop 0
	v_cvt_pk_bf16_f32 v99, v100, v101
	v_add_u32_e32 v100, 0x6000, v130
	ds_write2_b64 v100, v[122:123], v[98:99] offset0:96 offset1:100
	v_pk_mul_f32 v[98:99], v[94:95], v[94:95]
	s_nop 0
	v_fmamk_f32 v98, v98, 0xbdd2d3e2, v251
	v_fmamk_f32 v99, v99, 0xbdd2d3e2, v251
	v_mul_f32_e32 v98, v94, v98
	v_mul_f32_e32 v99, v95, v99
	v_exp_f32_e32 v98, v98
	v_exp_f32_e32 v99, v99
	v_add_f32_e32 v98, 1.0, v98
	v_add_f32_e32 v99, 1.0, v99
	v_rcp_f32_e32 v98, v98
	v_rcp_f32_e32 v99, v99
	s_nop 0
	v_pk_mul_f32 v[94:95], v[94:95], v[98:99]
	s_nop 0
	v_cvt_pk_bf16_f32 v98, v94, v95
	v_pk_add_f32 v[94:95], v[96:97], v[110:111]
	s_nop 0
	v_pk_mul_f32 v[96:97], v[94:95], v[94:95]
	s_nop 0
	v_fmamk_f32 v96, v96, 0xbdd2d3e2, v251
	v_fmamk_f32 v97, v97, 0xbdd2d3e2, v251
	v_mul_f32_e32 v96, v94, v96
	v_mul_f32_e32 v97, v95, v97
	v_exp_f32_e32 v96, v96
	v_exp_f32_e32 v97, v97
	v_add_f32_e32 v96, 1.0, v96
	v_add_f32_e32 v97, 1.0, v97
	v_rcp_f32_e32 v96, v96
	v_rcp_f32_e32 v97, v97
	s_nop 0
	v_pk_mul_f32 v[94:95], v[94:95], v[96:97]
	s_nop 0
	v_cvt_pk_bf16_f32 v99, v94, v95
	v_pk_mul_f32 v[94:95], v[90:91], v[90:91]
	s_nop 0
	v_fmamk_f32 v94, v94, 0xbdd2d3e2, v251
	v_fmamk_f32 v95, v95, 0xbdd2d3e2, v251
	v_mul_f32_e32 v94, v90, v94
	v_mul_f32_e32 v95, v91, v95
	v_exp_f32_e32 v94, v94
	v_exp_f32_e32 v95, v95
	v_add_f32_e32 v94, 1.0, v94
	v_add_f32_e32 v95, 1.0, v95
	v_rcp_f32_e32 v94, v94
	v_rcp_f32_e32 v95, v95
	s_nop 0
	v_pk_mul_f32 v[90:91], v[90:91], v[94:95]
	s_nop 0
	v_cvt_pk_bf16_f32 v94, v90, v91
	v_pk_add_f32 v[90:91], v[92:93], v[110:111]
	s_nop 0
	v_pk_mul_f32 v[92:93], v[90:91], v[90:91]
	s_nop 0
	v_fmamk_f32 v92, v92, 0xbdd2d3e2, v251
	v_fmamk_f32 v93, v93, 0xbdd2d3e2, v251
	v_mul_f32_e32 v92, v90, v92
	v_mul_f32_e32 v93, v91, v93
	v_exp_f32_e32 v92, v92
	v_exp_f32_e32 v93, v93
	v_add_f32_e32 v92, 1.0, v92
	v_add_f32_e32 v93, 1.0, v93
	v_rcp_f32_e32 v92, v92
	v_rcp_f32_e32 v93, v93
	s_nop 0
	v_pk_mul_f32 v[90:91], v[90:91], v[92:93]
	s_nop 0
	v_cvt_pk_bf16_f32 v95, v90, v91
	v_pk_mul_f32 v[90:91], v[86:87], v[86:87]
	s_nop 0
	v_fmamk_f32 v90, v90, 0xbdd2d3e2, v251
	v_fmamk_f32 v91, v91, 0xbdd2d3e2, v251
	v_mul_f32_e32 v90, v86, v90
	v_mul_f32_e32 v91, v87, v91
	v_exp_f32_e32 v90, v90
	v_exp_f32_e32 v91, v91
	v_add_f32_e32 v90, 1.0, v90
	v_add_f32_e32 v91, 1.0, v91
	v_rcp_f32_e32 v90, v90
	v_rcp_f32_e32 v91, v91
	s_nop 0
	v_pk_mul_f32 v[86:87], v[86:87], v[90:91]
	s_nop 0
	v_cvt_pk_bf16_f32 v90, v86, v87
	v_pk_add_f32 v[86:87], v[88:89], v[110:111]
	s_nop 0
	v_pk_mul_f32 v[88:89], v[86:87], v[86:87]
	s_nop 0
	v_fmamk_f32 v88, v88, 0xbdd2d3e2, v251
	v_fmamk_f32 v89, v89, 0xbdd2d3e2, v251
	v_mul_f32_e32 v88, v86, v88
	v_mul_f32_e32 v89, v87, v89
	v_exp_f32_e32 v88, v88
	v_exp_f32_e32 v89, v89
	v_add_f32_e32 v88, 1.0, v88
	v_add_f32_e32 v89, 1.0, v89
	v_rcp_f32_e32 v88, v88
	v_rcp_f32_e32 v89, v89
	s_nop 0
	v_pk_mul_f32 v[86:87], v[86:87], v[88:89]
	s_nop 0
	v_cvt_pk_bf16_f32 v91, v86, v87
	v_pk_mul_f32 v[86:87], v[82:83], v[82:83]
	s_nop 0
	v_fmamk_f32 v86, v86, 0xbdd2d3e2, v251
	v_fmamk_f32 v87, v87, 0xbdd2d3e2, v251
	v_mul_f32_e32 v86, v82, v86
	v_mul_f32_e32 v87, v83, v87
	v_exp_f32_e32 v86, v86
	v_exp_f32_e32 v87, v87
	v_add_f32_e32 v86, 1.0, v86
	v_add_f32_e32 v87, 1.0, v87
	v_rcp_f32_e32 v86, v86
	v_rcp_f32_e32 v87, v87
	s_nop 0
	v_pk_mul_f32 v[82:83], v[82:83], v[86:87]
	s_nop 0
	v_cvt_pk_bf16_f32 v86, v82, v83
	v_pk_add_f32 v[82:83], v[84:85], v[110:111]
	s_nop 0
	v_pk_mul_f32 v[84:85], v[82:83], v[82:83]
	s_nop 0
	v_fmamk_f32 v84, v84, 0xbdd2d3e2, v251
	v_fmamk_f32 v85, v85, 0xbdd2d3e2, v251
	v_mul_f32_e32 v84, v82, v84
	v_mul_f32_e32 v85, v83, v85
	v_exp_f32_e32 v84, v84
	v_exp_f32_e32 v85, v85
	v_add_f32_e32 v84, 1.0, v84
	v_add_f32_e32 v85, 1.0, v85
	v_rcp_f32_e32 v84, v84
	v_rcp_f32_e32 v85, v85
	s_nop 0
	v_pk_mul_f32 v[82:83], v[82:83], v[84:85]
	s_nop 0
	v_cvt_pk_bf16_f32 v87, v82, v83
	global_load_dwordx4 v[82:85], v[118:119], off offset:192
	s_waitcnt vmcnt(0)
	v_pk_add_f32 v[78:79], v[78:79], v[82:83]
	s_nop 0
	v_pk_mul_f32 v[88:89], v[78:79], v[78:79]
	v_pk_add_f32 v[80:81], v[80:81], v[84:85]
	v_fmamk_f32 v88, v88, 0xbdd2d3e2, v251
	v_fmamk_f32 v89, v89, 0xbdd2d3e2, v251
	v_mul_f32_e32 v88, v78, v88
	v_mul_f32_e32 v89, v79, v89
	v_exp_f32_e32 v88, v88
	v_exp_f32_e32 v89, v89
	v_pk_add_f32 v[74:75], v[74:75], v[82:83]
	v_pk_add_f32 v[76:77], v[76:77], v[84:85]
	v_add_f32_e32 v88, 1.0, v88
	v_add_f32_e32 v89, 1.0, v89
	v_rcp_f32_e32 v88, v88
	v_rcp_f32_e32 v89, v89
	v_pk_add_f32 v[70:71], v[70:71], v[82:83]
	v_pk_add_f32 v[72:73], v[72:73], v[84:85]
	v_pk_add_f32 v[66:67], v[66:67], v[82:83]
	v_pk_mul_f32 v[78:79], v[78:79], v[88:89]
	v_pk_mul_f32 v[88:89], v[80:81], v[80:81]
	v_cvt_pk_bf16_f32 v78, v78, v79
	v_fmamk_f32 v79, v88, 0xbdd2d3e2, v251
	v_mul_f32_e32 v79, v80, v79
	v_exp_f32_e32 v79, v79
	v_pk_add_f32 v[68:69], v[68:69], v[84:85]
	v_add_f32_e32 v79, 1.0, v79
	v_rcp_f32_e32 v88, v79
	v_fmamk_f32 v79, v89, 0xbdd2d3e2, v251
	v_mul_f32_e32 v79, v81, v79
	v_exp_f32_e32 v79, v79
	s_nop 0
	v_add_f32_e32 v79, 1.0, v79
	v_rcp_f32_e32 v89, v79
	s_nop 0
	v_pk_mul_f32 v[80:81], v[80:81], v[88:89]
	s_nop 0
	v_cvt_pk_bf16_f32 v79, v80, v81
	ds_write2_b64 v130, v[98:99], v[78:79] offset0:8 offset1:12
	v_pk_mul_f32 v[78:79], v[74:75], v[74:75]
	s_nop 0
	v_fmamk_f32 v78, v78, 0xbdd2d3e2, v251
	v_fmamk_f32 v79, v79, 0xbdd2d3e2, v251
	v_mul_f32_e32 v78, v74, v78
	v_mul_f32_e32 v79, v75, v79
	v_exp_f32_e32 v78, v78
	v_exp_f32_e32 v79, v79
	v_add_f32_e32 v78, 1.0, v78
	v_add_f32_e32 v79, 1.0, v79
	v_rcp_f32_e32 v78, v78
	v_rcp_f32_e32 v79, v79
	s_nop 0
	v_pk_mul_f32 v[74:75], v[74:75], v[78:79]
	v_pk_mul_f32 v[78:79], v[76:77], v[76:77]
	v_cvt_pk_bf16_f32 v74, v74, v75
	v_fmamk_f32 v75, v78, 0xbdd2d3e2, v251
	v_mul_f32_e32 v75, v76, v75
	v_exp_f32_e32 v75, v75
	s_nop 0
	v_add_f32_e32 v75, 1.0, v75
	v_rcp_f32_e32 v78, v75
	v_fmamk_f32 v75, v79, 0xbdd2d3e2, v251
	v_mul_f32_e32 v75, v77, v75
	v_exp_f32_e32 v75, v75
	s_nop 0
	v_add_f32_e32 v75, 1.0, v75
	v_rcp_f32_e32 v79, v75
	s_nop 0
	v_pk_mul_f32 v[76:77], v[76:77], v[78:79]
	s_nop 0
	v_cvt_pk_bf16_f32 v75, v76, v77
	ds_write2_b64 v106, v[94:95], v[74:75] offset0:40 offset1:44
	v_pk_mul_f32 v[74:75], v[70:71], v[70:71]
	s_nop 0
	v_fmamk_f32 v74, v74, 0xbdd2d3e2, v251
	v_fmamk_f32 v75, v75, 0xbdd2d3e2, v251
	v_mul_f32_e32 v74, v70, v74
	v_mul_f32_e32 v75, v71, v75
	v_exp_f32_e32 v74, v74
	v_exp_f32_e32 v75, v75
	v_add_f32_e32 v74, 1.0, v74
	v_add_f32_e32 v75, 1.0, v75
	v_rcp_f32_e32 v74, v74
	v_rcp_f32_e32 v75, v75
	s_nop 0
	v_pk_mul_f32 v[70:71], v[70:71], v[74:75]
	v_pk_mul_f32 v[74:75], v[72:73], v[72:73]
	v_cvt_pk_bf16_f32 v70, v70, v71
	v_fmamk_f32 v71, v74, 0xbdd2d3e2, v251
	v_mul_f32_e32 v71, v72, v71
	v_exp_f32_e32 v71, v71
	s_nop 0
	v_add_f32_e32 v71, 1.0, v71
	v_rcp_f32_e32 v74, v71
	v_fmamk_f32 v71, v75, 0xbdd2d3e2, v251
	v_mul_f32_e32 v71, v73, v71
	v_exp_f32_e32 v71, v71
	s_nop 0
	v_add_f32_e32 v71, 1.0, v71
	v_rcp_f32_e32 v75, v71
	s_nop 0
	v_pk_mul_f32 v[72:73], v[72:73], v[74:75]
	s_nop 0
	v_cvt_pk_bf16_f32 v71, v72, v73
	ds_write2_b64 v102, v[90:91], v[70:71] offset0:72 offset1:76
	v_pk_mul_f32 v[70:71], v[66:67], v[66:67]
	s_nop 0
	v_fmamk_f32 v70, v70, 0xbdd2d3e2, v251
	v_fmamk_f32 v71, v71, 0xbdd2d3e2, v251
	v_mul_f32_e32 v70, v66, v70
	v_mul_f32_e32 v71, v67, v71
	v_exp_f32_e32 v70, v70
	v_exp_f32_e32 v71, v71
	v_add_f32_e32 v70, 1.0, v70
	v_add_f32_e32 v71, 1.0, v71
	v_rcp_f32_e32 v70, v70
	v_rcp_f32_e32 v71, v71
	s_nop 0
	v_pk_mul_f32 v[66:67], v[66:67], v[70:71]
	v_pk_mul_f32 v[70:71], v[68:69], v[68:69]
	v_cvt_pk_bf16_f32 v66, v66, v67
	v_fmamk_f32 v67, v70, 0xbdd2d3e2, v251
	v_mul_f32_e32 v67, v68, v67
	v_exp_f32_e32 v67, v67
	s_nop 0
	v_add_f32_e32 v67, 1.0, v67
	v_rcp_f32_e32 v70, v67
	v_fmamk_f32 v67, v71, 0xbdd2d3e2, v251
	v_mul_f32_e32 v67, v69, v67
	v_exp_f32_e32 v67, v67
	s_nop 0
	v_add_f32_e32 v67, 1.0, v67
	v_rcp_f32_e32 v71, v67
	s_nop 0
	v_pk_mul_f32 v[68:69], v[68:69], v[70:71]
	s_nop 0
	v_cvt_pk_bf16_f32 v67, v68, v69
	global_load_dwordx4 v[68:71], v[118:119], off offset:256
	ds_write2_b64 v100, v[86:87], v[66:67] offset0:104 offset1:108
	s_waitcnt vmcnt(0)
	v_pk_add_f32 v[62:63], v[62:63], v[68:69]
	s_nop 0
	v_pk_mul_f32 v[66:67], v[62:63], v[62:63]
	v_pk_add_f32 v[58:59], v[58:59], v[68:69]
	v_fmamk_f32 v66, v66, 0xbdd2d3e2, v251
	v_fmamk_f32 v67, v67, 0xbdd2d3e2, v251
	v_mul_f32_e32 v66, v62, v66
	v_mul_f32_e32 v67, v63, v67
	v_exp_f32_e32 v66, v66
	v_exp_f32_e32 v67, v67
	v_pk_add_f32 v[54:55], v[54:55], v[68:69]
	v_pk_add_f32 v[50:51], v[50:51], v[68:69]
	v_add_f32_e32 v66, 1.0, v66
	v_add_f32_e32 v67, 1.0, v67
	v_rcp_f32_e32 v66, v66
	v_rcp_f32_e32 v67, v67
	s_nop 0
	v_pk_mul_f32 v[62:63], v[62:63], v[66:67]
	s_nop 0
	v_cvt_pk_bf16_f32 v66, v62, v63
	v_pk_add_f32 v[62:63], v[64:65], v[70:71]
	s_nop 0
	v_pk_mul_f32 v[64:65], v[62:63], v[62:63]
	s_nop 0
	v_fmamk_f32 v64, v64, 0xbdd2d3e2, v251
	v_fmamk_f32 v65, v65, 0xbdd2d3e2, v251
	v_mul_f32_e32 v64, v62, v64
	v_mul_f32_e32 v65, v63, v65
	v_exp_f32_e32 v64, v64
	v_exp_f32_e32 v65, v65
	v_add_f32_e32 v64, 1.0, v64
	v_add_f32_e32 v65, 1.0, v65
	v_rcp_f32_e32 v64, v64
	v_rcp_f32_e32 v65, v65
	s_nop 0
	v_pk_mul_f32 v[62:63], v[62:63], v[64:65]
	s_nop 0
	v_cvt_pk_bf16_f32 v67, v62, v63
	v_pk_mul_f32 v[62:63], v[58:59], v[58:59]
	s_nop 0
	v_fmamk_f32 v62, v62, 0xbdd2d3e2, v251
	v_fmamk_f32 v63, v63, 0xbdd2d3e2, v251
	v_mul_f32_e32 v62, v58, v62
	v_mul_f32_e32 v63, v59, v63
	v_exp_f32_e32 v62, v62
	v_exp_f32_e32 v63, v63
	v_add_f32_e32 v62, 1.0, v62
	v_add_f32_e32 v63, 1.0, v63
	v_rcp_f32_e32 v62, v62
	v_rcp_f32_e32 v63, v63
	s_nop 0
	v_pk_mul_f32 v[58:59], v[58:59], v[62:63]
	s_nop 0
	v_cvt_pk_bf16_f32 v62, v58, v59
	v_pk_add_f32 v[58:59], v[60:61], v[70:71]
	s_nop 0
	v_pk_mul_f32 v[60:61], v[58:59], v[58:59]
	s_nop 0
	v_fmamk_f32 v60, v60, 0xbdd2d3e2, v251
	v_fmamk_f32 v61, v61, 0xbdd2d3e2, v251
	v_mul_f32_e32 v60, v58, v60
	v_mul_f32_e32 v61, v59, v61
	v_exp_f32_e32 v60, v60
	v_exp_f32_e32 v61, v61
	v_add_f32_e32 v60, 1.0, v60
	v_add_f32_e32 v61, 1.0, v61
	v_rcp_f32_e32 v60, v60
	v_rcp_f32_e32 v61, v61
	s_nop 0
	v_pk_mul_f32 v[58:59], v[58:59], v[60:61]
	s_nop 0
	v_cvt_pk_bf16_f32 v63, v58, v59
	v_pk_mul_f32 v[58:59], v[54:55], v[54:55]
	s_nop 0
	v_fmamk_f32 v58, v58, 0xbdd2d3e2, v251
	v_fmamk_f32 v59, v59, 0xbdd2d3e2, v251
	v_mul_f32_e32 v58, v54, v58
	v_mul_f32_e32 v59, v55, v59
	v_exp_f32_e32 v58, v58
	v_exp_f32_e32 v59, v59
	v_add_f32_e32 v58, 1.0, v58
	v_add_f32_e32 v59, 1.0, v59
	v_rcp_f32_e32 v58, v58
	v_rcp_f32_e32 v59, v59
	s_nop 0
	v_pk_mul_f32 v[54:55], v[54:55], v[58:59]
	s_nop 0
	v_cvt_pk_bf16_f32 v58, v54, v55
	v_pk_add_f32 v[54:55], v[56:57], v[70:71]
	s_nop 0
	v_pk_mul_f32 v[56:57], v[54:55], v[54:55]
	s_nop 0
	v_fmamk_f32 v56, v56, 0xbdd2d3e2, v251
	v_fmamk_f32 v57, v57, 0xbdd2d3e2, v251
	v_mul_f32_e32 v56, v54, v56
	v_mul_f32_e32 v57, v55, v57
	v_exp_f32_e32 v56, v56
	v_exp_f32_e32 v57, v57
	v_add_f32_e32 v56, 1.0, v56
	v_add_f32_e32 v57, 1.0, v57
	v_rcp_f32_e32 v56, v56
	v_rcp_f32_e32 v57, v57
	s_nop 0
	v_pk_mul_f32 v[54:55], v[54:55], v[56:57]
	s_nop 0
	v_cvt_pk_bf16_f32 v59, v54, v55
	v_pk_mul_f32 v[54:55], v[50:51], v[50:51]
	s_nop 0
	v_fmamk_f32 v54, v54, 0xbdd2d3e2, v251
	v_fmamk_f32 v55, v55, 0xbdd2d3e2, v251
	v_mul_f32_e32 v54, v50, v54
	v_mul_f32_e32 v55, v51, v55
	v_exp_f32_e32 v54, v54
	v_exp_f32_e32 v55, v55
	v_add_f32_e32 v54, 1.0, v54
	v_add_f32_e32 v55, 1.0, v55
	v_rcp_f32_e32 v54, v54
	v_rcp_f32_e32 v55, v55
	s_nop 0
	v_pk_mul_f32 v[50:51], v[50:51], v[54:55]
	s_nop 0
	v_cvt_pk_bf16_f32 v54, v50, v51
	v_pk_add_f32 v[50:51], v[52:53], v[70:71]
	s_nop 0
	v_pk_mul_f32 v[52:53], v[50:51], v[50:51]
	s_nop 0
	v_fmamk_f32 v52, v52, 0xbdd2d3e2, v251
	v_fmamk_f32 v53, v53, 0xbdd2d3e2, v251
	v_mul_f32_e32 v52, v50, v52
	v_mul_f32_e32 v53, v51, v53
	v_exp_f32_e32 v52, v52
	v_exp_f32_e32 v53, v53
	v_add_f32_e32 v52, 1.0, v52
	v_add_f32_e32 v53, 1.0, v53
	v_rcp_f32_e32 v52, v52
	v_rcp_f32_e32 v53, v53
	s_nop 0
	v_pk_mul_f32 v[50:51], v[50:51], v[52:53]
	s_nop 0
	v_cvt_pk_bf16_f32 v55, v50, v51
	global_load_dwordx4 v[50:53], v[118:119], off offset:320
	s_waitcnt vmcnt(0)
	v_pk_add_f32 v[46:47], v[46:47], v[50:51]
	s_nop 0
	v_pk_mul_f32 v[56:57], v[46:47], v[46:47]
	v_pk_add_f32 v[48:49], v[48:49], v[52:53]
	v_fmamk_f32 v56, v56, 0xbdd2d3e2, v251
	v_fmamk_f32 v57, v57, 0xbdd2d3e2, v251
	v_mul_f32_e32 v56, v46, v56
	v_mul_f32_e32 v57, v47, v57
	v_exp_f32_e32 v56, v56
	v_exp_f32_e32 v57, v57
	v_pk_add_f32 v[42:43], v[42:43], v[50:51]
	v_pk_add_f32 v[44:45], v[44:45], v[52:53]
	v_add_f32_e32 v56, 1.0, v56
	v_add_f32_e32 v57, 1.0, v57
	v_rcp_f32_e32 v56, v56
	v_rcp_f32_e32 v57, v57
	v_pk_add_f32 v[38:39], v[38:39], v[50:51]
	v_pk_add_f32 v[40:41], v[40:41], v[52:53]
	v_pk_add_f32 v[34:35], v[34:35], v[50:51]
	v_pk_mul_f32 v[46:47], v[46:47], v[56:57]
	v_pk_mul_f32 v[56:57], v[48:49], v[48:49]
	v_cvt_pk_bf16_f32 v46, v46, v47
	v_fmamk_f32 v47, v56, 0xbdd2d3e2, v251
	v_mul_f32_e32 v47, v48, v47
	v_exp_f32_e32 v47, v47
	v_pk_add_f32 v[36:37], v[36:37], v[52:53]
	v_add_f32_e32 v47, 1.0, v47
	v_rcp_f32_e32 v56, v47
	v_fmamk_f32 v47, v57, 0xbdd2d3e2, v251
	v_mul_f32_e32 v47, v49, v47
	v_exp_f32_e32 v47, v47
	s_nop 0
	v_add_f32_e32 v47, 1.0, v47
	v_rcp_f32_e32 v57, v47
	s_nop 0
	v_pk_mul_f32 v[48:49], v[48:49], v[56:57]
	s_nop 0
	v_cvt_pk_bf16_f32 v47, v48, v49
	ds_write2_b64 v130, v[66:67], v[46:47] offset0:16 offset1:20
	v_pk_mul_f32 v[46:47], v[42:43], v[42:43]
	s_nop 0
	v_fmamk_f32 v46, v46, 0xbdd2d3e2, v251
	v_fmamk_f32 v47, v47, 0xbdd2d3e2, v251
	v_mul_f32_e32 v46, v42, v46
	v_mul_f32_e32 v47, v43, v47
	v_exp_f32_e32 v46, v46
	v_exp_f32_e32 v47, v47
	v_add_f32_e32 v46, 1.0, v46
	v_add_f32_e32 v47, 1.0, v47
	v_rcp_f32_e32 v46, v46
	v_rcp_f32_e32 v47, v47
	s_nop 0
	v_pk_mul_f32 v[42:43], v[42:43], v[46:47]
	v_pk_mul_f32 v[46:47], v[44:45], v[44:45]
	v_cvt_pk_bf16_f32 v42, v42, v43
	v_fmamk_f32 v43, v46, 0xbdd2d3e2, v251
	v_mul_f32_e32 v43, v44, v43
	v_exp_f32_e32 v43, v43
	s_nop 0
	v_add_f32_e32 v43, 1.0, v43
	v_rcp_f32_e32 v46, v43
	v_fmamk_f32 v43, v47, 0xbdd2d3e2, v251
	v_mul_f32_e32 v43, v45, v43
	v_exp_f32_e32 v43, v43
	s_nop 0
	v_add_f32_e32 v43, 1.0, v43
	v_rcp_f32_e32 v47, v43
	s_nop 0
	v_pk_mul_f32 v[44:45], v[44:45], v[46:47]
	s_nop 0
	v_cvt_pk_bf16_f32 v43, v44, v45
	ds_write2_b64 v106, v[62:63], v[42:43] offset0:48 offset1:52
	v_pk_mul_f32 v[42:43], v[38:39], v[38:39]
	s_nop 0
	v_fmamk_f32 v42, v42, 0xbdd2d3e2, v251
	v_fmamk_f32 v43, v43, 0xbdd2d3e2, v251
	v_mul_f32_e32 v42, v38, v42
	v_mul_f32_e32 v43, v39, v43
	v_exp_f32_e32 v42, v42
	v_exp_f32_e32 v43, v43
	v_add_f32_e32 v42, 1.0, v42
	v_add_f32_e32 v43, 1.0, v43
	v_rcp_f32_e32 v42, v42
	v_rcp_f32_e32 v43, v43
	s_nop 0
	v_pk_mul_f32 v[38:39], v[38:39], v[42:43]
	v_pk_mul_f32 v[42:43], v[40:41], v[40:41]
	v_cvt_pk_bf16_f32 v38, v38, v39
	v_fmamk_f32 v39, v42, 0xbdd2d3e2, v251
	v_mul_f32_e32 v39, v40, v39
	v_exp_f32_e32 v39, v39
	s_nop 0
	v_add_f32_e32 v39, 1.0, v39
	v_rcp_f32_e32 v42, v39
	v_fmamk_f32 v39, v43, 0xbdd2d3e2, v251
	v_mul_f32_e32 v39, v41, v39
	v_exp_f32_e32 v39, v39
	s_nop 0
	v_add_f32_e32 v39, 1.0, v39
	v_rcp_f32_e32 v43, v39
	s_nop 0
	v_pk_mul_f32 v[40:41], v[40:41], v[42:43]
	s_nop 0
	v_cvt_pk_bf16_f32 v39, v40, v41
	ds_write2_b64 v102, v[58:59], v[38:39] offset0:80 offset1:84
	v_pk_mul_f32 v[38:39], v[34:35], v[34:35]
	s_nop 0
	v_fmamk_f32 v38, v38, 0xbdd2d3e2, v251
	v_fmamk_f32 v39, v39, 0xbdd2d3e2, v251
	v_mul_f32_e32 v38, v34, v38
	v_mul_f32_e32 v39, v35, v39
	v_exp_f32_e32 v38, v38
	v_exp_f32_e32 v39, v39
	v_add_f32_e32 v38, 1.0, v38
	v_add_f32_e32 v39, 1.0, v39
	v_rcp_f32_e32 v38, v38
	v_rcp_f32_e32 v39, v39
	s_nop 0
	v_pk_mul_f32 v[34:35], v[34:35], v[38:39]
	v_pk_mul_f32 v[38:39], v[36:37], v[36:37]
	v_cvt_pk_bf16_f32 v34, v34, v35
	v_fmamk_f32 v35, v38, 0xbdd2d3e2, v251
	v_mul_f32_e32 v35, v36, v35
	v_exp_f32_e32 v35, v35
	s_nop 0
	v_add_f32_e32 v35, 1.0, v35
	v_rcp_f32_e32 v38, v35
	v_fmamk_f32 v35, v39, 0xbdd2d3e2, v251
	v_mul_f32_e32 v35, v37, v35
	v_exp_f32_e32 v35, v35
	s_nop 0
	v_add_f32_e32 v35, 1.0, v35
	v_rcp_f32_e32 v39, v35
	s_nop 0
	v_pk_mul_f32 v[36:37], v[36:37], v[38:39]
	s_nop 0
	v_cvt_pk_bf16_f32 v35, v36, v37
	global_load_dwordx4 v[36:39], v[118:119], off offset:384
	ds_write2_b64 v100, v[54:55], v[34:35] offset0:112 offset1:116
	s_waitcnt vmcnt(0)
	v_pk_add_f32 v[30:31], v[30:31], v[36:37]
	s_nop 0
	v_pk_mul_f32 v[34:35], v[30:31], v[30:31]
	v_pk_add_f32 v[26:27], v[26:27], v[36:37]
	v_fmamk_f32 v34, v34, 0xbdd2d3e2, v251
	v_fmamk_f32 v35, v35, 0xbdd2d3e2, v251
	v_mul_f32_e32 v34, v30, v34
	v_mul_f32_e32 v35, v31, v35
	v_exp_f32_e32 v34, v34
	v_exp_f32_e32 v35, v35
	v_pk_add_f32 v[22:23], v[22:23], v[36:37]
	v_pk_add_f32 v[18:19], v[18:19], v[36:37]
	v_add_f32_e32 v34, 1.0, v34
	v_add_f32_e32 v35, 1.0, v35
	v_rcp_f32_e32 v34, v34
	v_rcp_f32_e32 v35, v35
	s_nop 0
	v_pk_mul_f32 v[30:31], v[30:31], v[34:35]
	s_nop 0
	v_cvt_pk_bf16_f32 v34, v30, v31
	v_pk_add_f32 v[30:31], v[32:33], v[38:39]
	s_nop 0
	v_pk_mul_f32 v[32:33], v[30:31], v[30:31]
	s_nop 0
	v_fmamk_f32 v32, v32, 0xbdd2d3e2, v251
	v_fmamk_f32 v33, v33, 0xbdd2d3e2, v251
	v_mul_f32_e32 v32, v30, v32
	v_mul_f32_e32 v33, v31, v33
	v_exp_f32_e32 v32, v32
	v_exp_f32_e32 v33, v33
	v_add_f32_e32 v32, 1.0, v32
	v_add_f32_e32 v33, 1.0, v33
	v_rcp_f32_e32 v32, v32
	v_rcp_f32_e32 v33, v33
	s_nop 0
	v_pk_mul_f32 v[30:31], v[30:31], v[32:33]
	s_nop 0
	v_cvt_pk_bf16_f32 v35, v30, v31
	v_pk_mul_f32 v[30:31], v[26:27], v[26:27]
	s_nop 0
	v_fmamk_f32 v30, v30, 0xbdd2d3e2, v251
	v_fmamk_f32 v31, v31, 0xbdd2d3e2, v251
	v_mul_f32_e32 v30, v26, v30
	v_mul_f32_e32 v31, v27, v31
	v_exp_f32_e32 v30, v30
	v_exp_f32_e32 v31, v31
	v_add_f32_e32 v30, 1.0, v30
	v_add_f32_e32 v31, 1.0, v31
	v_rcp_f32_e32 v30, v30
	v_rcp_f32_e32 v31, v31
	s_nop 0
	v_pk_mul_f32 v[26:27], v[26:27], v[30:31]
	s_nop 0
	v_cvt_pk_bf16_f32 v30, v26, v27
	v_pk_add_f32 v[26:27], v[28:29], v[38:39]
	s_nop 0
	v_pk_mul_f32 v[28:29], v[26:27], v[26:27]
	s_nop 0
	v_fmamk_f32 v28, v28, 0xbdd2d3e2, v251
	v_fmamk_f32 v29, v29, 0xbdd2d3e2, v251
	v_mul_f32_e32 v28, v26, v28
	v_mul_f32_e32 v29, v27, v29
	v_exp_f32_e32 v28, v28
	v_exp_f32_e32 v29, v29
	v_add_f32_e32 v28, 1.0, v28
	v_add_f32_e32 v29, 1.0, v29
	v_rcp_f32_e32 v28, v28
	v_rcp_f32_e32 v29, v29
	s_nop 0
	v_pk_mul_f32 v[26:27], v[26:27], v[28:29]
	s_nop 0
	v_cvt_pk_bf16_f32 v31, v26, v27
	v_pk_mul_f32 v[26:27], v[22:23], v[22:23]
	s_nop 0
	v_fmamk_f32 v26, v26, 0xbdd2d3e2, v251
	v_fmamk_f32 v27, v27, 0xbdd2d3e2, v251
	v_mul_f32_e32 v26, v22, v26
	v_mul_f32_e32 v27, v23, v27
	v_exp_f32_e32 v26, v26
	v_exp_f32_e32 v27, v27
	v_add_f32_e32 v26, 1.0, v26
	v_add_f32_e32 v27, 1.0, v27
	v_rcp_f32_e32 v26, v26
	v_rcp_f32_e32 v27, v27
	s_nop 0
	v_pk_mul_f32 v[22:23], v[22:23], v[26:27]
	s_nop 0
	v_cvt_pk_bf16_f32 v26, v22, v23
	v_pk_add_f32 v[22:23], v[24:25], v[38:39]
	s_nop 0
	v_pk_mul_f32 v[24:25], v[22:23], v[22:23]
	s_nop 0
	v_fmamk_f32 v24, v24, 0xbdd2d3e2, v251
	v_fmamk_f32 v25, v25, 0xbdd2d3e2, v251
	v_mul_f32_e32 v24, v22, v24
	v_mul_f32_e32 v25, v23, v25
	v_exp_f32_e32 v24, v24
	v_exp_f32_e32 v25, v25
	v_add_f32_e32 v24, 1.0, v24
	v_add_f32_e32 v25, 1.0, v25
	v_rcp_f32_e32 v24, v24
	v_rcp_f32_e32 v25, v25
	s_nop 0
	v_pk_mul_f32 v[22:23], v[22:23], v[24:25]
	s_nop 0
	v_cvt_pk_bf16_f32 v27, v22, v23
	v_pk_mul_f32 v[22:23], v[18:19], v[18:19]
	s_nop 0
	v_fmamk_f32 v22, v22, 0xbdd2d3e2, v251
	v_fmamk_f32 v23, v23, 0xbdd2d3e2, v251
	v_mul_f32_e32 v22, v18, v22
	v_mul_f32_e32 v23, v19, v23
	v_exp_f32_e32 v22, v22
	v_exp_f32_e32 v23, v23
	v_add_f32_e32 v22, 1.0, v22
	v_add_f32_e32 v23, 1.0, v23
	v_rcp_f32_e32 v22, v22
	v_rcp_f32_e32 v23, v23
	s_nop 0
	v_pk_mul_f32 v[18:19], v[18:19], v[22:23]
	s_nop 0
	v_cvt_pk_bf16_f32 v22, v18, v19
	v_pk_add_f32 v[18:19], v[20:21], v[38:39]
	s_nop 0
	v_pk_mul_f32 v[20:21], v[18:19], v[18:19]
	s_nop 0
	v_fmamk_f32 v20, v20, 0xbdd2d3e2, v251
	v_fmamk_f32 v21, v21, 0xbdd2d3e2, v251
	v_mul_f32_e32 v20, v18, v20
	v_mul_f32_e32 v21, v19, v21
	v_exp_f32_e32 v20, v20
	v_exp_f32_e32 v21, v21
	v_add_f32_e32 v20, 1.0, v20
	v_add_f32_e32 v21, 1.0, v21
	v_rcp_f32_e32 v20, v20
	v_rcp_f32_e32 v21, v21
	s_nop 0
	v_pk_mul_f32 v[18:19], v[18:19], v[20:21]
	s_nop 0
	v_cvt_pk_bf16_f32 v23, v18, v19
	global_load_dwordx4 v[18:21], v[118:119], off offset:448
	s_waitcnt vmcnt(0)
	v_pk_add_f32 v[14:15], v[14:15], v[18:19]
	s_nop 0
	v_pk_mul_f32 v[24:25], v[14:15], v[14:15]
	v_pk_add_f32 v[16:17], v[16:17], v[20:21]
	v_fmamk_f32 v24, v24, 0xbdd2d3e2, v251
	v_fmamk_f32 v25, v25, 0xbdd2d3e2, v251
	v_mul_f32_e32 v24, v14, v24
	v_mul_f32_e32 v25, v15, v25
	v_exp_f32_e32 v24, v24
	v_exp_f32_e32 v25, v25
	v_pk_add_f32 v[10:11], v[10:11], v[18:19]
	v_pk_add_f32 v[12:13], v[12:13], v[20:21]
	v_add_f32_e32 v24, 1.0, v24
	v_add_f32_e32 v25, 1.0, v25
	v_rcp_f32_e32 v24, v24
	v_rcp_f32_e32 v25, v25
	v_pk_add_f32 v[6:7], v[6:7], v[18:19]
	v_pk_add_f32 v[8:9], v[8:9], v[20:21]
	v_pk_add_f32 v[2:3], v[2:3], v[18:19]
	v_pk_mul_f32 v[14:15], v[14:15], v[24:25]
	v_pk_mul_f32 v[24:25], v[16:17], v[16:17]
	v_cvt_pk_bf16_f32 v14, v14, v15
	v_fmamk_f32 v15, v24, 0xbdd2d3e2, v251
	v_mul_f32_e32 v15, v16, v15
	v_exp_f32_e32 v15, v15
	v_pk_add_f32 v[4:5], v[4:5], v[20:21]
	v_add_f32_e32 v15, 1.0, v15
	v_rcp_f32_e32 v24, v15
	v_fmamk_f32 v15, v25, 0xbdd2d3e2, v251
	v_mul_f32_e32 v15, v17, v15
	v_exp_f32_e32 v15, v15
	s_nop 0
	v_add_f32_e32 v15, 1.0, v15
	v_rcp_f32_e32 v25, v15
	s_nop 0
	v_pk_mul_f32 v[16:17], v[16:17], v[24:25]
	s_nop 0
	v_cvt_pk_bf16_f32 v15, v16, v17
	ds_write2_b64 v130, v[34:35], v[14:15] offset0:24 offset1:28
	v_pk_mul_f32 v[14:15], v[10:11], v[10:11]
	v_and_b32_e32 v34, 15, v129
	v_fmamk_f32 v14, v14, 0xbdd2d3e2, v251
	v_fmamk_f32 v15, v15, 0xbdd2d3e2, v251
	v_mul_f32_e32 v14, v10, v14
	v_mul_f32_e32 v15, v11, v15
	v_exp_f32_e32 v14, v14
	v_exp_f32_e32 v15, v15
	v_add_f32_e32 v14, 1.0, v14
	v_add_f32_e32 v15, 1.0, v15
	v_rcp_f32_e32 v14, v14
	v_rcp_f32_e32 v15, v15
	s_nop 0
	v_pk_mul_f32 v[10:11], v[10:11], v[14:15]
	v_pk_mul_f32 v[14:15], v[12:13], v[12:13]
	v_cvt_pk_bf16_f32 v10, v10, v11
	v_fmamk_f32 v11, v14, 0xbdd2d3e2, v251
	v_mul_f32_e32 v11, v12, v11
	v_exp_f32_e32 v11, v11
	s_nop 0
	v_add_f32_e32 v11, 1.0, v11
	v_rcp_f32_e32 v14, v11
	v_fmamk_f32 v11, v15, 0xbdd2d3e2, v251
	v_mul_f32_e32 v11, v13, v11
	v_exp_f32_e32 v11, v11
	s_nop 0
	v_add_f32_e32 v11, 1.0, v11
	v_rcp_f32_e32 v15, v11
	s_nop 0
	v_pk_mul_f32 v[12:13], v[12:13], v[14:15]
	s_nop 0
	v_cvt_pk_bf16_f32 v11, v12, v13
	ds_write2_b64 v106, v[30:31], v[10:11] offset0:56 offset1:60
	v_pk_mul_f32 v[10:11], v[6:7], v[6:7]
	s_nop 0
	v_fmamk_f32 v10, v10, 0xbdd2d3e2, v251
	v_fmamk_f32 v11, v11, 0xbdd2d3e2, v251
	v_mul_f32_e32 v10, v6, v10
	v_mul_f32_e32 v11, v7, v11
	v_exp_f32_e32 v10, v10
	v_exp_f32_e32 v11, v11
	v_add_f32_e32 v10, 1.0, v10
	v_add_f32_e32 v11, 1.0, v11
	v_rcp_f32_e32 v10, v10
	v_rcp_f32_e32 v11, v11
	s_nop 0
	v_pk_mul_f32 v[6:7], v[6:7], v[10:11]
	v_pk_mul_f32 v[10:11], v[8:9], v[8:9]
	v_cvt_pk_bf16_f32 v6, v6, v7
	v_fmamk_f32 v7, v10, 0xbdd2d3e2, v251
	v_mul_f32_e32 v7, v8, v7
	v_exp_f32_e32 v7, v7
	s_nop 0
	v_add_f32_e32 v7, 1.0, v7
	v_rcp_f32_e32 v10, v7
	v_fmamk_f32 v7, v11, 0xbdd2d3e2, v251
	v_mul_f32_e32 v7, v9, v7
	v_exp_f32_e32 v7, v7
	s_nop 0
	v_add_f32_e32 v7, 1.0, v7
	v_rcp_f32_e32 v11, v7
	s_nop 0
	v_pk_mul_f32 v[8:9], v[8:9], v[10:11]
	s_nop 0
	v_cvt_pk_bf16_f32 v7, v8, v9
	ds_write2_b64 v102, v[26:27], v[6:7] offset0:88 offset1:92
	v_pk_mul_f32 v[6:7], v[2:3], v[2:3]
	v_lshl_add_u64 v[10:11], s[40:41], 0, v[0:1]
	v_fmamk_f32 v6, v6, 0xbdd2d3e2, v251
	v_fmamk_f32 v7, v7, 0xbdd2d3e2, v251
	v_mul_f32_e32 v6, v2, v6
	v_mul_f32_e32 v7, v3, v7
	v_exp_f32_e32 v6, v6
	v_exp_f32_e32 v7, v7
	v_lshl_add_u64 v[68:69], v[10:11], 0, 64
	v_add_f32_e32 v6, 1.0, v6
	v_add_f32_e32 v7, 1.0, v7
	v_rcp_f32_e32 v6, v6
	v_rcp_f32_e32 v7, v7
	s_nop 0
	v_pk_mul_f32 v[2:3], v[2:3], v[6:7]
	v_pk_mul_f32 v[6:7], v[4:5], v[4:5]
	v_cvt_pk_bf16_f32 v2, v2, v3
	v_fmamk_f32 v3, v6, 0xbdd2d3e2, v251
	v_mul_f32_e32 v3, v4, v3
	v_exp_f32_e32 v3, v3
	s_nop 0
	v_add_f32_e32 v3, 1.0, v3
	v_rcp_f32_e32 v6, v3
	v_fmamk_f32 v3, v7, 0xbdd2d3e2, v251
	v_mul_f32_e32 v3, v5, v3
	v_exp_f32_e32 v3, v3
	s_nop 0
	v_add_f32_e32 v3, 1.0, v3
	v_rcp_f32_e32 v7, v3
	s_nop 0
	v_pk_mul_f32 v[4:5], v[4:5], v[6:7]
	s_nop 0
	v_cvt_pk_bf16_f32 v3, v4, v5
	ds_write2_b64 v100, v[22:23], v[2:3] offset0:120 offset1:124
	v_ashrrev_i32_e32 v2, 1, v129
	v_and_b32_e32 v35, 0xffffffe0, v2
	v_or_b32_e32 v2, v35, v34
	v_lshlrev_b32_e32 v6, 9, v34
	v_mad_u64_u32 v[12:13], s[0:1], v2, s0, v[0:1]
	v_mov_b32_e32 v7, v1
	v_or_b32_e32 v2, 0x2000, v6
	v_mov_b32_e32 v3, v1
	v_lshl_add_u64 v[8:9], v[10:11], 0, v[6:7]
	v_lshl_add_u64 v[4:5], v[10:11], 0, v[2:3]
	s_waitcnt lgkmcnt(0)
	s_barrier
	ds_read_b128 v[14:17], v12
	ds_read_b128 v[18:21], v12 offset:8448
	global_load_dwordx4 v[22:25], v[8:9], off
	global_load_dwordx4 v[26:29], v[4:5], off
	v_or_b32_e32 v4, 0x4000, v6
	v_mov_b32_e32 v5, v1
	v_or_b32_e32 v6, 0x6000, v6
	v_lshl_add_u64 v[30:31], v[10:11], 0, v[4:5]
	v_lshl_add_u64 v[36:37], v[10:11], 0, v[6:7]
	global_load_dwordx4 v[30:33], v[30:31], off
	v_lshl_add_u64 v[60:61], v[68:69], 0, v[2:3]
	global_load_dwordx4 v[36:39], v[36:37], off
	v_lshl_add_u64 v[64:65], v[68:69], 0, v[4:5]
	v_lshl_add_u64 v[68:69], v[68:69], 0, v[6:7]
	s_waitcnt vmcnt(3) lgkmcnt(1)
	v_mfma_f32_16x16x32_bf16 v[40:43], v[22:25], v[14:17], 0
	s_mov_b64 s[0:1], 0xc0
	v_or_b32_e32 v34, s12, v34
	s_mov_b64 s[12:13], -1
	s_waitcnt lgkmcnt(0)
	v_mfma_f32_16x16x32_bf16 v[22:25], v[22:25], v[18:21], 0
	s_waitcnt vmcnt(2)
	v_mfma_f32_16x16x32_bf16 v[44:47], v[26:29], v[14:17], 0
	v_mfma_f32_16x16x32_bf16 v[26:29], v[26:29], v[18:21], 0
	s_waitcnt vmcnt(1)
	v_mfma_f32_16x16x32_bf16 v[48:51], v[30:33], v[14:17], 0
	v_mfma_f32_16x16x32_bf16 v[30:33], v[30:33], v[18:21], 0
	s_waitcnt vmcnt(0)
	v_mfma_f32_16x16x32_bf16 v[14:17], v[36:39], v[14:17], 0
	v_mfma_f32_16x16x32_bf16 v[18:21], v[36:39], v[18:21], 0
	ds_read_b128 v[36:39], v12 offset:64
	ds_read_b128 v[52:55], v12 offset:8512
	global_load_dwordx4 v[64:67], v[64:65], off
	s_nop 0
	global_load_dwordx4 v[68:71], v[68:69], off
	s_waitcnt vmcnt(0) lgkmcnt(1)
	v_mfma_f32_16x16x32_bf16 v[14:17], v[68:71], v[36:39], v[14:17]
	global_load_dwordx4 v[56:59], v[8:9], off offset:64
	s_nop 0
	global_load_dwordx4 v[60:63], v[60:61], off
	s_waitcnt lgkmcnt(0)
	v_mfma_f32_16x16x32_bf16 v[18:21], v[68:71], v[52:55], v[18:21]
	v_lshl_add_u64 v[68:69], v[10:11], 0, s[6:7]
	s_waitcnt vmcnt(0)
	v_mfma_f32_16x16x32_bf16 v[44:47], v[60:63], v[36:39], v[44:47]
	v_mfma_f32_16x16x32_bf16 v[26:29], v[60:63], v[52:55], v[26:29]
	v_lshl_add_u64 v[60:61], v[68:69], 0, v[2:3]
	v_mfma_f32_16x16x32_bf16 v[48:51], v[64:67], v[36:39], v[48:51]
	v_mfma_f32_16x16x32_bf16 v[30:33], v[64:67], v[52:55], v[30:33]
	v_lshl_add_u64 v[64:65], v[68:69], 0, v[4:5]
	v_lshl_add_u64 v[68:69], v[68:69], 0, v[6:7]
	v_mfma_f32_16x16x32_bf16 v[40:43], v[56:59], v[36:39], v[40:43]
	v_mfma_f32_16x16x32_bf16 v[22:25], v[56:59], v[52:55], v[22:25]
	ds_read_b128 v[36:39], v12 offset:128
	ds_read_b128 v[52:55], v12 offset:8576
	global_load_dwordx4 v[64:67], v[64:65], off
	s_nop 0
	global_load_dwordx4 v[68:71], v[68:69], off
	s_waitcnt vmcnt(0) lgkmcnt(1)
	v_mfma_f32_16x16x32_bf16 v[14:17], v[68:71], v[36:39], v[14:17]
	global_load_dwordx4 v[56:59], v[8:9], off offset:128
	s_nop 0
	global_load_dwordx4 v[60:63], v[60:61], off
	s_waitcnt lgkmcnt(0)
	v_mfma_f32_16x16x32_bf16 v[18:21], v[68:71], v[52:55], v[18:21]
	v_lshl_add_u64 v[68:69], v[10:11], 0, s[0:1]
	s_mov_b64 s[0:1], 0x100
	s_waitcnt vmcnt(0)
	v_mfma_f32_16x16x32_bf16 v[44:47], v[60:63], v[36:39], v[44:47]
	v_mfma_f32_16x16x32_bf16 v[26:29], v[60:63], v[52:55], v[26:29]
	v_lshl_add_u64 v[60:61], v[68:69], 0, v[2:3]
	v_mfma_f32_16x16x32_bf16 v[48:51], v[64:67], v[36:39], v[48:51]
	v_mfma_f32_16x16x32_bf16 v[30:33], v[64:67], v[52:55], v[30:33]
	v_lshl_add_u64 v[64:65], v[68:69], 0, v[4:5]
	v_lshl_add_u64 v[68:69], v[68:69], 0, v[6:7]
	v_mfma_f32_16x16x32_bf16 v[40:43], v[56:59], v[36:39], v[40:43]
	v_mfma_f32_16x16x32_bf16 v[22:25], v[56:59], v[52:55], v[22:25]
	ds_read_b128 v[36:39], v12 offset:192
	ds_read_b128 v[52:55], v12 offset:8640
	global_load_dwordx4 v[64:67], v[64:65], off
	s_nop 0
	global_load_dwordx4 v[68:71], v[68:69], off
	s_waitcnt vmcnt(0) lgkmcnt(1)
	v_mfma_f32_16x16x32_bf16 v[14:17], v[68:71], v[36:39], v[14:17]
	global_load_dwordx4 v[56:59], v[8:9], off offset:192
	s_nop 0
	global_load_dwordx4 v[60:63], v[60:61], off
	s_waitcnt lgkmcnt(0)
	v_mfma_f32_16x16x32_bf16 v[18:21], v[68:71], v[52:55], v[18:21]
	v_lshl_add_u64 v[68:69], v[10:11], 0, s[0:1]
	s_mov_b64 s[0:1], 0x140
	s_waitcnt vmcnt(0)
	v_mfma_f32_16x16x32_bf16 v[44:47], v[60:63], v[36:39], v[44:47]
	v_mfma_f32_16x16x32_bf16 v[26:29], v[60:63], v[52:55], v[26:29]
	v_lshl_add_u64 v[60:61], v[68:69], 0, v[2:3]
	v_mfma_f32_16x16x32_bf16 v[48:51], v[64:67], v[36:39], v[48:51]
	v_mfma_f32_16x16x32_bf16 v[30:33], v[64:67], v[52:55], v[30:33]
	v_lshl_add_u64 v[64:65], v[68:69], 0, v[4:5]
	v_lshl_add_u64 v[68:69], v[68:69], 0, v[6:7]
	v_mfma_f32_16x16x32_bf16 v[40:43], v[56:59], v[36:39], v[40:43]
	v_mfma_f32_16x16x32_bf16 v[22:25], v[56:59], v[52:55], v[22:25]
	ds_read_b128 v[36:39], v12 offset:256
	ds_read_b128 v[52:55], v12 offset:8704
	global_load_dwordx4 v[64:67], v[64:65], off
	s_nop 0
	global_load_dwordx4 v[68:71], v[68:69], off
	s_waitcnt vmcnt(0) lgkmcnt(1)
	v_mfma_f32_16x16x32_bf16 v[14:17], v[68:71], v[36:39], v[14:17]
	global_load_dwordx4 v[56:59], v[8:9], off offset:256
	s_nop 0
	global_load_dwordx4 v[60:63], v[60:61], off
	s_waitcnt lgkmcnt(0)
	v_mfma_f32_16x16x32_bf16 v[18:21], v[68:71], v[52:55], v[18:21]
	v_lshl_add_u64 v[68:69], v[10:11], 0, s[0:1]
	s_mov_b64 s[0:1], 0x180
	s_waitcnt vmcnt(0)
	v_mfma_f32_16x16x32_bf16 v[44:47], v[60:63], v[36:39], v[44:47]
	v_mfma_f32_16x16x32_bf16 v[26:29], v[60:63], v[52:55], v[26:29]
	v_lshl_add_u64 v[60:61], v[68:69], 0, v[2:3]
	v_mfma_f32_16x16x32_bf16 v[48:51], v[64:67], v[36:39], v[48:51]
	v_mfma_f32_16x16x32_bf16 v[30:33], v[64:67], v[52:55], v[30:33]
	v_lshl_add_u64 v[64:65], v[68:69], 0, v[4:5]
	v_lshl_add_u64 v[68:69], v[68:69], 0, v[6:7]
	v_mfma_f32_16x16x32_bf16 v[40:43], v[56:59], v[36:39], v[40:43]
	v_mfma_f32_16x16x32_bf16 v[22:25], v[56:59], v[52:55], v[22:25]
	ds_read_b128 v[36:39], v12 offset:320
	ds_read_b128 v[52:55], v12 offset:8768
	global_load_dwordx4 v[64:67], v[64:65], off
	s_nop 0
	global_load_dwordx4 v[68:71], v[68:69], off
	s_waitcnt vmcnt(0) lgkmcnt(1)
	v_mfma_f32_16x16x32_bf16 v[14:17], v[68:71], v[36:39], v[14:17]
	global_load_dwordx4 v[56:59], v[8:9], off offset:320
	s_nop 0
	global_load_dwordx4 v[60:63], v[60:61], off
	s_waitcnt lgkmcnt(0)
	v_mfma_f32_16x16x32_bf16 v[18:21], v[68:71], v[52:55], v[18:21]
	v_lshl_add_u64 v[68:69], v[10:11], 0, s[0:1]
	s_mov_b64 s[0:1], 0x1c0
	s_waitcnt vmcnt(0)
	v_mfma_f32_16x16x32_bf16 v[44:47], v[60:63], v[36:39], v[44:47]
	v_mfma_f32_16x16x32_bf16 v[26:29], v[60:63], v[52:55], v[26:29]
	v_lshl_add_u64 v[60:61], v[68:69], 0, v[2:3]
	v_mfma_f32_16x16x32_bf16 v[48:51], v[64:67], v[36:39], v[48:51]
	v_mfma_f32_16x16x32_bf16 v[30:33], v[64:67], v[52:55], v[30:33]
	v_lshl_add_u64 v[64:65], v[68:69], 0, v[4:5]
	v_lshl_add_u64 v[68:69], v[68:69], 0, v[6:7]
	v_mfma_f32_16x16x32_bf16 v[40:43], v[56:59], v[36:39], v[40:43]
	v_mfma_f32_16x16x32_bf16 v[22:25], v[56:59], v[52:55], v[22:25]
	ds_read_b128 v[36:39], v12 offset:384
	ds_read_b128 v[52:55], v12 offset:8832
	global_load_dwordx4 v[56:59], v[8:9], off offset:384
	s_nop 0
	global_load_dwordx4 v[60:63], v[60:61], off
	s_waitcnt vmcnt(1) lgkmcnt(1)
	v_mfma_f32_16x16x32_bf16 v[40:43], v[56:59], v[36:39], v[40:43]
	global_load_dwordx4 v[64:67], v[64:65], off
	s_nop 0
	global_load_dwordx4 v[68:71], v[68:69], off
	s_waitcnt vmcnt(2)
	v_mfma_f32_16x16x32_bf16 v[44:47], v[60:63], v[36:39], v[44:47]
	s_waitcnt vmcnt(1)
	v_mfma_f32_16x16x32_bf16 v[48:51], v[64:67], v[36:39], v[48:51]
	s_waitcnt vmcnt(0)
	v_mfma_f32_16x16x32_bf16 v[36:39], v[68:71], v[36:39], v[14:17]
	s_nop 2
	v_lshl_add_u64 v[16:17], v[10:11], 0, s[0:1]
	v_lshl_add_u64 v[2:3], v[16:17], 0, v[2:3]
	v_lshl_add_u64 v[6:7], v[16:17], 0, v[6:7]
	s_waitcnt lgkmcnt(0)
	v_mfma_f32_16x16x32_bf16 v[22:25], v[56:59], v[52:55], v[22:25]
	s_cselect_b64 s[0:1], -1, 0
	s_and_b64 vcc, exec, s[0:1]
	v_mfma_f32_16x16x32_bf16 v[56:59], v[60:63], v[52:55], v[26:29]
	v_mfma_f32_16x16x32_bf16 v[60:63], v[64:67], v[52:55], v[30:33]
	v_mfma_f32_16x16x32_bf16 v[52:55], v[68:71], v[52:55], v[18:21]
	ds_read_b128 v[64:67], v12 offset:448
	ds_read_b128 v[68:71], v12 offset:8896
	global_load_dwordx4 v[8:11], v[8:9], off offset:448
	s_nop 0
	global_load_dwordx4 v[12:15], v[2:3], off
	global_load_dwordx4 v[72:75], v[6:7], off
	v_lshl_add_u64 v[2:3], v[16:17], 0, v[4:5]
	global_load_dwordx4 v[2:5], v[2:3], off
	s_waitcnt vmcnt(3) lgkmcnt(1)
	v_mfma_f32_16x16x32_bf16 v[30:33], v[8:11], v[64:67], v[40:43]
	s_nop 2
	v_or_b32_e32 v43, 3, v128
	s_waitcnt lgkmcnt(0)
	v_mfma_f32_16x16x32_bf16 v[26:29], v[8:11], v[68:71], v[22:25]
	s_waitcnt vmcnt(1)
	v_mfma_f32_16x16x32_bf16 v[6:9], v[72:75], v[64:67], v[36:39]
	s_nop 2
	v_add_u32_e32 v39, v34, v35
	v_ashrrev_i32_e32 v34, 9, v39
	v_mfma_f32_16x16x32_bf16 v[22:25], v[12:15], v[64:67], v[44:47]
	v_bfi_b32 v34, -4, v34, v129
	v_ashrrev_i32_e32 v35, 31, v34
	v_lshlrev_b64 v[36:37], 15, v[34:35]
	v_mfma_f32_16x16x32_bf16 v[18:21], v[12:15], v[68:71], v[56:59]
	v_lshrrev_b32_e32 v47, 2, v39
	v_and_b32_e32 v40, 0x1fb, v47
	v_lshlrev_b32_e32 v38, 1, v39
	s_waitcnt vmcnt(0)
	v_mfma_f32_16x16x32_bf16 v[14:17], v[2:5], v[64:67], v[48:51]
	v_lshrrev_b32_e32 v34, 3, v39
	v_bfe_u32 v35, v39, 2, 2
	v_lshlrev_b32_e32 v39, 2, v40
	v_mfma_f32_16x16x32_bf16 v[10:13], v[2:5], v[68:71], v[60:63]
	v_or_b32_e32 v45, 1, v128
	v_or_b32_e32 v44, 2, v128
	v_and_b32_e32 v46, 0xe00, v38
	v_mfma_f32_16x16x32_bf16 v[2:5], v[72:75], v[68:71], v[52:55]
	v_and_or_b32 v40, v34, 4, v35
	v_and_b32_e32 v41, 0xc0, v39
	v_lshl_add_u64 v[34:35], v[36:37], 1, s[48:49]
	s_cbranch_vccz .LBB0_599
	v_or3_b32 v42, v128, v46, v41
	v_lshlrev_b32_e32 v48, 4, v42
	v_mov_b32_e32 v49, v1
	v_lshl_add_u64 v[48:49], v[34:35], 0, v[48:49]
	v_lshlrev_b32_e32 v50, 1, v40
	v_mov_b32_e32 v51, v1
	v_cvt_pk_bf16_f32 v39, v30, s0
	v_lshl_add_u64 v[48:49], v[48:49], 0, v[50:51]
	v_or3_b32 v42, v45, v46, v41
	global_store_short v[48:49], v39, off
	v_lshlrev_b32_e32 v48, 4, v42
	v_mov_b32_e32 v49, v1
	v_lshl_add_u64 v[48:49], v[34:35], 0, v[48:49]
	v_cvt_pk_bf16_f32 v39, v31, s0
	v_lshl_add_u64 v[48:49], v[48:49], 0, v[50:51]
	v_or3_b32 v42, v44, v46, v41
	global_store_short v[48:49], v39, off
	v_lshlrev_b32_e32 v48, 4, v42
	v_mov_b32_e32 v49, v1
	v_lshl_add_u64 v[48:49], v[34:35], 0, v[48:49]
	v_cvt_pk_bf16_f32 v39, v32, s0
	v_lshl_add_u64 v[48:49], v[48:49], 0, v[50:51]
	v_or3_b32 v42, v43, v46, v41
	global_store_short v[48:49], v39, off
	v_lshlrev_b32_e32 v48, 4, v42
	v_mov_b32_e32 v49, v1
	v_lshl_add_u64 v[48:49], v[34:35], 0, v[48:49]
	v_cvt_pk_bf16_f32 v39, v33, s0
	v_lshl_add_u64 v[48:49], v[48:49], 0, v[50:51]
	global_store_short v[48:49], v39, off
	s_mov_b64 s[12:13], 0
